# deferred layer-1 weight transposes in the layer-0 mixer phase are paced (s_sleep 16 per two tiles): they have slack and were competing with the critical hyena jobs
# baseline (speedup 1.0000x reference)
; __device__ __forceinline__ TrJob tr_decode(const Params& p, char* ws, int job) {
;   TrJob t;
;   int l = job / TJ_PER_LAYER, rj = job % TJ_PER_LAYER;
;   if (rj < 640) {
;     t.src = p.w_in + (size_t)l * 1024 * 2560; t.K = 1024; t.N = 2560; t.kt = rj / 40; t.nt = rj % 40;
;     t.dst = (u16*)(ws + OFF_WINT) + (size_t)l * 2560 * 1024; t.mode = 0;
;   } else if (rj < 896) {
;     rj -= 640;
;     t.src = p.w_out + (size_t)l * 1024 * 1024; t.K = 1024; t.N = 1024; t.kt = rj / 16; t.nt = rj % 16;
;     t.dst = (u16*)(ws + OFF_WOUTT) + (size_t)l * 1024 * 1024; t.mode = 0;
;   } else {
;     rj -= 896;
;     int e = rj / 1536, q = rj % 1536;
;     size_t eo = (size_t)(l * 16 + e);
;     if (q < 512) {
;       t.src = p.w_gate + eo * 1024 * 2048; t.K = 1024; t.N = 2048; t.kt = q / 32; t.nt = q % 32;
;       t.dst = (u16*)(ws + OFF_WGUT) + eo * 4096 * 1024; t.mode = 1;
;     } else if (q < 1024) {
;       q -= 512;
;       t.src = p.w_up + eo * 1024 * 2048; t.K = 1024; t.N = 2048; t.kt = q / 32; t.nt = q % 32;
;       t.dst = (u16*)(ws + OFF_WGUT) + eo * 4096 * 1024; t.mode = 2;
;     } else {
;       q -= 1024;
;       t.src = p.w_down + eo * 2048 * 1024; t.K = 2048; t.N = 1024; t.kt = q / 16; t.nt = q % 16;
;       t.dst = (u16*)(ws + OFF_WDT) + eo * 1024 * 2048; t.mode = 0;
;     }
;   }
; __device__ __forceinline__ void p0_transposes(const Params& p, char* smem, int bid, int nb, int jlo, int jhi) {
;     ...
;   for (; j < jhi; j += 2 * nb) {
;     const int jn = j + 2 * nb;
;     if (jn < jhi) { tr_load(p, ws, jn, tid, n0); tr_load(p, ws, jn + 1, tid, n1); }
;     tr_lds_write(tileA, tid, c0);
;     tr_lds_write(tileB, tid, c1);
;     __syncthreads();
.LBB0_787:
	s_sleep 16
	v_add_u32_e32 v0, 0x1040, v70
	s_waitcnt vmcnt(0)
	ds_write2_b32 v70, v18, v19 offset1:1
	ds_write2_b32 v70, v20, v21 offset0:2 offset1:3
	ds_write2_b32 v0, v22, v23 offset1:1
	v_add_u32_e32 v0, 0x1048, v70
	ds_write2_b32 v0, v24, v25 offset1:1
	v_add_u32_e32 v0, 0x2080, v70
	ds_write2_b32 v0, v26, v27 offset1:1
	v_add_u32_e32 v0, 0x2088, v70
	ds_write2_b32 v0, v28, v29 offset1:1
	v_add_u32_e32 v0, 0x30c0, v70
	ds_write2_b32 v0, v30, v31 offset1:1
	v_add_u32_e32 v0, 0x30c8, v70
	ds_write2_b32 v0, v32, v33 offset1:1
	v_add_u32_e32 v0, 0x4100, v70
	ds_write2_b32 v0, v50, v51 offset1:1
	v_add_u32_e32 v0, 0x4108, v70
	ds_write2_b32 v0, v52, v53 offset1:1
	v_add_u32_e32 v0, 0x5140, v70
	s_mul_hi_i32 s10, s22, 0x5254e78f
	ds_write2_b32 v0, v54, v55 offset1:1
	v_add_u32_e32 v0, 0x5148, v70
	s_lshr_b32 s11, s10, 31
	s_ashr_i32 s10, s10, 13
	ds_write2_b32 v0, v56, v57 offset1:1
	v_add_u32_e32 v0, 0x6180, v70
	s_add_i32 s12, s10, s11
	ds_write2_b32 v0, v58, v59 offset1:1
	v_add_u32_e32 v0, 0x6188, v70
	s_mul_i32 s10, s12, 0xffff9c80
	ds_write2_b32 v0, v60, v61 offset1:1
	v_add_u32_e32 v0, 0x71c0, v70
	s_add_i32 s30, s22, s10
	ds_write2_b32 v0, v62, v63 offset1:1
	v_add_u32_e32 v0, 0x71c8, v70
	s_cmpk_gt_i32 s30, 0x27f
	s_mov_b64 s[18:19], -1
	ds_write2_b32 v0, v64, v65 offset1:1
	s_waitcnt lgkmcnt(0)
	s_barrier
	s_cbranch_scc0 .LBB0_800
	s_cmpk_gt_u32 s30, 0x37f
	s_cbranch_scc0 .LBB0_797
	s_add_i32 s10, s30, 0xfc80
	s_and_b32 s11, s10, 0xffff
	s_mul_i32 s11, s11, 0xaaab
	s_lshr_b32 s11, s11, 26
	s_mul_i32 s13, s11, 0x600
	s_sub_i32 s10, s10, s13
	s_and_b32 s35, s10, 0xffff
	s_lshl_b32 s10, s12, 4
	s_add_i32 s18, s10, s11
	s_ashr_i32 s19, s18, 31
	s_cmpk_gt_u32 s35, 0x1ff
	s_mov_b64 s[20:21], -1
	s_cbranch_scc0 .LBB0_794
	s_mov_b64 s[10:11], -1
	s_cmpk_gt_u32 s35, 0x3ff
	s_mov_b64 s[14:15], -1
	s_cbranch_scc0 .LBB0_792
	s_add_i32 s13, s35, 0xfffffc00
	s_lshr_b32 s31, s13, 4
	s_and_b32 s34, s35, 15
	s_lshl_b64 s[14:15], s[18:19], 22
	s_add_u32 s16, s23, s14
	s_addc_u32 s17, s24, s15
	s_mov_b64 s[14:15], 0
